# GLU touch prefetch moved into the first load segment with a counted vmcnt(7): the touch gets about 1.75 K-tiles before an in-order wait needs it
# baseline (speedup 1.0000x reference)
;     __device__ __forceinline__ size_t a_off(const Unit& u) const { return (size_t)u.pm * atile; }
;     __device__ __forceinline__ size_t b_off(const Unit& u) const { return (size_t)u.pn * btile; }
;     __device__ __forceinline__ size_t a_off(const Unit& u) const { return ((size_t)u.g * NROW + (size_t)u.pm * BM) * KA * 2; }
;     __device__ __forceinline__ size_t b_off(const Unit& u) const { return (size_t)u.g * btile; }
;     __device__ __forceinline__ size_t a_off(const Unit& u) const { return ((size_t)u.g * NROW + (size_t)u.pm * BM) * KA * 2; }
;     __device__ __forceinline__ size_t b_off(const Unit& u) const { return (size_t)u.g * btile; }
; #define PG8_STAGE(bufoff, gbase, voff) do { const __amdgpu_buffer_rsrc_t _r = __builtin_amdgcn_make_buffer_rsrc((void*)(gbase), (short)0, 0x7fffffff, 0x00020000); _Pragma("unroll") for (int _i = 0; _i < 2; ++_i) \
;         __builtin_amdgcn_raw_ptr_buffer_load_lds(_r, (LAS unsigned*)(lds + (bufoff) + ldsw + _i * 8192), 16, (int)(voff)[_i], 0, 0, 0); } while (0)
; #define PG8_LDA(dst, b, h) do { _Pragma("unroll") for (int m = 0; m < 4; ++m) _Pragma("unroll") for (int k = 0; k < 2; ++k) dst[m][k] = *(const LAS bf16x8*)(lds + PG8_SA(b, h) + aoff + m * 2048 + k * 1024); } while (0)
; #define PG8_WAIT_L(n) asm volatile("s_waitcnt lgkmcnt(" #n ")" ::: "memory")
;     ...
;         const char* nA = has_next ? (const char*)Ap + S.a_off(nxt) : cA; const char* nB = has_next ? (const char*)Btp + S.b_off(nxt) : cB;
;         for (int t = 0; t < nt; t += 2) {
;             const bool last = (t == nt - 2);
;             const char* a1 = cA + (size_t)(t + 1) * kstep;
;             const char* a2 = last ? nA : cA + (size_t)(t + 2) * kstep; const char* b2 = last ? nB : cB + (size_t)(t + 2) * kstep;
;             const char* a3 = a2 + kstep; const char* b3 = b2 + kstep;
;             PG8_LDB(B0, 0, 0); PG8_SCHED; PG8_LDA(At, 0, 0); PG8_STAGE(PG8_SA(1, 1), a1 + hstepA, voffA);
;             PG8_WAIT_L(8); PG8_BAR; PG8_WAIT_L(0); PG8_MMA(0, 0, At, B0); PG8_BAR; PG8_SCHED;
;             PG8_LDB(B1, 0, 1); PG8_STAGE(PG8_SB(0, 0), b2, voffB);
;             PG8_BAR; PG8_WAIT_L(0); PG8_MMA(0, 1, At, B1); PG8_BAR;
;             PG8_LDA(At, 0, 1); PG8_STAGE(PG8_SA(0, 0), a2, voffA);
;             PG8_BAR; PG8_WAIT_L(0); PG8_MMA(1, 0, At, B0); PG8_BAR; PG8_SCHED;
;             PG8_STAGE(PG8_SB(0, 1), b2 + hstepB, voffB);
.LBB0_625:
	s_ashr_i32 s97, s96, 31
	s_lshl_b64 s[8:9], s[96:97], 19
	s_add_u32 s68, s40, s8
	s_addc_u32 s69, s41, s9
	s_ashr_i32 s95, s94, 31
	s_lshl_b64 s[8:9], s[94:95], 19
	s_add_u32 s12, s3, s8
	v_cmp_lt_i64_e64 s[0:1], s[0:1], v[184:185]
	s_addc_u32 s13, s87, s9
	s_andn2_b64 vcc, exec, s[36:37]
	s_waitcnt lgkmcnt(0)
	s_cbranch_vccnz .Lkzero_627
	s_and_b64 s[0:1], s[0:1], exec
	s_cselect_b32 s0, s69, s27
	s_cselect_b32 s1, s68, s26
	s_cselect_b32 s47, s13, s25
	s_cselect_b32 s51, s12, s24
	s_add_u32 s89, s26, 0x100
	s_addc_u32 s90, s27, 0
	s_add_u32 s91, s24, 0x100
	s_mov_b64 s[44:45], s[36:37]
	s_addc_u32 s92, s25, 0
	s_mov_b32 s8, 0
	v_readlane_b32 s98, v252, 6
	v_readlane_b32 s99, v252, 7
	v_lshrrev_b32_e32 v226, 4, v232
	v_and_b32_e32 v226, 0x1c, v226
	v_bfe_u32 v227, v232, 2, 2
	v_or_b32_e32 v226, v226, v227
	v_lshl_add_u32 v226, s66, 8, v226
	v_lshlrev_b32_e32 v226, 12, v226
	v_and_b32_e32 v227, 3, v232
	v_lshl_add_u32 v226, v227, 7, v226
	v_lshl_add_u32 v230, s64, 9, v226
	v_mov_b32_e32 v231, 0
	v_mov_b32_e32 v228, 0x20000
	v_mov_b32_e32 v229, 0
	v_lshl_add_u64 v[226:227], v[230:231], 0, s[98:99]
	ds_read_b128 v[128:131], v212
	ds_read_b128 v[132:135], v212 offset:1024
	ds_read_b128 v[136:139], v212 offset:2048
	ds_read_b128 v[140:143], v212 offset:3072
	s_add_i32 s16, s8, 2
	s_cmp_eq_u32 s82, s8
	s_cselect_b32 s36, s1, s89
	s_cselect_b32 s23, s0, s90
	s_cselect_b32 s22, s47, s92
	s_cselect_b32 s28, s51, s91
	s_add_u32 s24, s36, 0x80
	s_addc_u32 s17, s23, 0
	s_add_u32 s8, s89, s18
	s_addc_u32 s9, s90, s19
	s_add_u32 s8, s8, 0xffffff80
	s_addc_u32 s9, s9, -1
	s_and_b32 s9, s9, 0xffff
	s_mov_b32 m0, s83
	ds_read_b128 v[144:147], v213
	ds_read_b128 v[148:151], v213 offset:1024
	ds_read_b128 v[152:155], v213 offset:2048
	ds_read_b128 v[156:159], v213 offset:3072
	ds_read_b128 v[160:163], v213 offset:4096
	ds_read_b128 v[164:167], v213 offset:5120
	ds_read_b128 v[168:171], v213 offset:6144
	ds_read_b128 v[172:175], v213 offset:7168
	buffer_load_dwordx4 v206, s[8:11], 0 offen lds
	s_mov_b32 m0, s84
	s_nop 0
	buffer_load_dwordx4 v208, s[8:11], 0 offen lds
	s_mov_b32 exec_lo, 0xffff
	s_mov_b32 exec_hi, 0
	global_load_dword v230, v[226:227], off
	s_mov_b64 exec, -1
	v_lshl_add_u64 v[226:227], v[228:229], 0, v[226:227]
	s_waitcnt lgkmcnt(8)
	s_barrier
	s_waitcnt lgkmcnt(0)
	s_setprio 1
	s_waitcnt lgkmcnt(7)
	v_mfma_f32_16x16x32_bf16 v[112:115], v[128:131], v[144:147], 0
	v_mfma_f32_16x16x32_bf16 v[116:119], v[136:139], v[144:147], 0
	s_waitcnt lgkmcnt(5)
	v_mfma_f32_16x16x32_bf16 v[100:103], v[128:131], v[152:155], 0
	v_mfma_f32_16x16x32_bf16 v[96:99], v[136:139], v[152:155], 0
	s_waitcnt lgkmcnt(3)
	v_mfma_f32_16x16x32_bf16 v[84:87], v[128:131], v[160:163], 0
	v_mfma_f32_16x16x32_bf16 v[80:83], v[136:139], v[160:163], 0
	s_waitcnt lgkmcnt(1)
	v_mfma_f32_16x16x32_bf16 v[68:71], v[128:131], v[168:171], 0
	v_mfma_f32_16x16x32_bf16 v[64:67], v[136:139], v[168:171], 0
	v_mfma_f32_16x16x32_bf16 v[112:115], v[132:135], v[148:151], v[112:115]
	v_mfma_f32_16x16x32_bf16 v[116:119], v[140:143], v[148:151], v[116:119]
	v_mfma_f32_16x16x32_bf16 v[100:103], v[132:135], v[156:159], v[100:103]
	v_mfma_f32_16x16x32_bf16 v[96:99], v[140:143], v[156:159], v[96:99]
	v_mfma_f32_16x16x32_bf16 v[84:87], v[132:135], v[164:167], v[84:87]
	v_mfma_f32_16x16x32_bf16 v[80:83], v[140:143], v[164:167], v[80:83]
	s_waitcnt lgkmcnt(0)
	v_mfma_f32_16x16x32_bf16 v[68:71], v[132:135], v[172:175], v[68:71]
	v_mfma_f32_16x16x32_bf16 v[64:67], v[140:143], v[172:175], v[64:67]
	s_setprio 0
	s_barrier
	s_and_b32 s29, s22, 0xffff
	s_mov_b32 s30, s10
	s_mov_b32 s31, s11
	s_mov_b32 m0, s15
	ds_read_b128 v[176:179], v214
	ds_read_b128 v[180:183], v214 offset:1024
	ds_read_b128 v[188:191], v214 offset:2048
	ds_read_b128 v[192:195], v214 offset:3072
	buffer_load_dwordx4 v207, s[28:31], 0 offen lds
	s_mov_b32 m0, s33
	s_nop 0
	buffer_load_dwordx4 v209, s[28:31], 0 offen lds
	s_barrier
	s_waitcnt lgkmcnt(0)
	s_setprio 1
	s_waitcnt lgkmcnt(3)
	v_mfma_f32_16x16x32_bf16 v[124:127], v[176:179], v[144:147], 0
	s_waitcnt lgkmcnt(1)
	v_mfma_f32_16x16x32_bf16 v[120:123], v[188:191], v[144:147], 0
	v_mfma_f32_16x16x32_bf16 v[108:111], v[176:179], v[152:155], 0
	v_mfma_f32_16x16x32_bf16 v[104:107], v[188:191], v[152:155], 0
	v_mfma_f32_16x16x32_bf16 v[92:95], v[176:179], v[160:163], 0
	v_mfma_f32_16x16x32_bf16 v[88:91], v[188:191], v[160:163], 0
	v_mfma_f32_16x16x32_bf16 v[76:79], v[176:179], v[168:171], 0
	v_mfma_f32_16x16x32_bf16 v[72:75], v[188:191], v[168:171], 0
	v_mfma_f32_16x16x32_bf16 v[124:127], v[180:183], v[148:151], v[124:127]
	s_waitcnt lgkmcnt(0)
	v_mfma_f32_16x16x32_bf16 v[120:123], v[192:195], v[148:151], v[120:123]
	v_mfma_f32_16x16x32_bf16 v[108:111], v[180:183], v[156:159], v[108:111]
	v_mfma_f32_16x16x32_bf16 v[104:107], v[192:195], v[156:159], v[104:107]
	v_mfma_f32_16x16x32_bf16 v[92:95], v[180:183], v[164:167], v[92:95]
	v_mfma_f32_16x16x32_bf16 v[88:91], v[192:195], v[164:167], v[88:91]
	v_mfma_f32_16x16x32_bf16 v[76:79], v[180:183], v[172:175], v[76:79]
	v_mfma_f32_16x16x32_bf16 v[72:75], v[192:195], v[172:175], v[72:75]
	s_setprio 0
	s_and_b32 s37, s23, 0xffff
	s_mov_b32 s38, s10
	s_mov_b32 s39, s11
	s_mov_b32 m0, s14
	s_barrier
	ds_read_b128 v[144:147], v213 offset:16384
	ds_read_b128 v[148:151], v213 offset:17408
	ds_read_b128 v[152:155], v213 offset:18432
	ds_read_b128 v[156:159], v213 offset:19456
	ds_read_b128 v[160:163], v213 offset:20480
	ds_read_b128 v[164:167], v213 offset:21504
	ds_read_b128 v[168:171], v213 offset:22528
	ds_read_b128 v[172:175], v213 offset:23552
	buffer_load_dwordx4 v206, s[36:39], 0 offen lds
	s_mov_b32 m0, s35
	s_nop 0
	buffer_load_dwordx4 v208, s[36:39], 0 offen lds
	s_barrier
; #define PG8_STAGE(bufoff, gbase, voff) do { const __amdgpu_buffer_rsrc_t _r = __builtin_amdgcn_make_buffer_rsrc((void*)(gbase), (short)0, 0x7fffffff, 0x00020000); _Pragma("unroll") for (int _i = 0; _i < 2; ++_i) \
;         __builtin_amdgcn_raw_ptr_buffer_load_lds(_r, (LAS unsigned*)(lds + (bufoff) + ldsw + _i * 8192), 16, (int)(voff)[_i], 0, 0, 0); } while (0)
; #define PG8_LDA(dst, b, h) do { _Pragma("unroll") for (int m = 0; m < 4; ++m) _Pragma("unroll") for (int k = 0; k < 2; ++k) dst[m][k] = *(const LAS bf16x8*)(lds + PG8_SA(b, h) + aoff + m * 2048 + k * 1024); } while (0)
; #define PG8_LDB(dst, b, h) do { _Pragma("unroll") for (int n = 0; n < 2; ++n) _Pragma("unroll") for (int k = 0; k < 2; ++k) dst[n][k] = *(const LAS bf16x8*)(lds + PG8_SB(b, h) + boff + n * 2048 + k * 1024); } while (0)
; #define PG8_MMA(ai, bj, At, Bt) do { __builtin_amdgcn_s_setprio(1); _Pragma("unroll") for (int k = 0; k < 2; ++k) _Pragma("unroll") for (int m = 0; m < 4; ++m) _Pragma("unroll") for (int n = 0; n < ((bj) == 1 ? NB1 : 2); ++n) \
;         acc[ai][bj][m][n] = __builtin_amdgcn_mfma_f32_16x16x32_bf16(Bt[n][k], At[m][k], acc[ai][bj][m][n], 0, 0, 0); __builtin_amdgcn_s_setprio(0); } while (0)
; #define PG8_WAIT_V(n) asm volatile("s_waitcnt vmcnt(" #n ")" ::: "memory")
; #define PG8_WAIT_L(n) asm volatile("s_waitcnt lgkmcnt(" #n ")" ::: "memory")
; #define PG8_BAR __builtin_amdgcn_s_barrier()
; #define PG8_SCHED __builtin_amdgcn_sched_barrier(0)
;     ...
;             PG8_STAGE(PG8_SB(0, 1), b2 + hstepB, voffB);
;             PG8_WAIT_V(6); PG8_BAR; PG8_MMA(1, 1, At, B1); PG8_BAR;
;             PG8_LDB(B0, 1, 0); PG8_SCHED; PG8_LDA(At, 1, 0); PG8_STAGE(PG8_SA(0, 1), a2 + hstepA, voffA);
;             PG8_WAIT_L(8); PG8_BAR; PG8_WAIT_L(0); PG8_MMA(0, 0, At, B0); PG8_BAR; PG8_SCHED;
	s_waitcnt lgkmcnt(0)
	s_setprio 1
	s_waitcnt lgkmcnt(7)
	v_mfma_f32_16x16x32_bf16 v[52:55], v[128:131], v[144:147], 0
	v_mfma_f32_16x16x32_bf16 v[48:51], v[136:139], v[144:147], 0
	s_waitcnt lgkmcnt(5)
	v_mfma_f32_16x16x32_bf16 v[36:39], v[128:131], v[152:155], 0
	v_mfma_f32_16x16x32_bf16 v[32:35], v[136:139], v[152:155], 0
	s_waitcnt lgkmcnt(3)
	v_mfma_f32_16x16x32_bf16 v[20:23], v[128:131], v[160:163], 0
	v_mfma_f32_16x16x32_bf16 v[16:19], v[136:139], v[160:163], 0
	s_waitcnt lgkmcnt(1)
	v_mfma_f32_16x16x32_bf16 v[4:7], v[128:131], v[168:171], 0
	v_mfma_f32_16x16x32_bf16 v[0:3], v[136:139], v[168:171], 0
	v_mfma_f32_16x16x32_bf16 v[52:55], v[132:135], v[148:151], v[52:55]
	v_mfma_f32_16x16x32_bf16 v[48:51], v[140:143], v[148:151], v[48:51]
	v_mfma_f32_16x16x32_bf16 v[36:39], v[132:135], v[156:159], v[36:39]
	v_mfma_f32_16x16x32_bf16 v[32:35], v[140:143], v[156:159], v[32:35]
	v_mfma_f32_16x16x32_bf16 v[20:23], v[132:135], v[164:167], v[20:23]
	v_mfma_f32_16x16x32_bf16 v[16:19], v[140:143], v[164:167], v[16:19]
	s_waitcnt lgkmcnt(0)
	v_mfma_f32_16x16x32_bf16 v[4:7], v[132:135], v[172:175], v[4:7]
	v_mfma_f32_16x16x32_bf16 v[0:3], v[140:143], v[172:175], v[0:3]
	s_setprio 0
	s_barrier
	s_add_u32 s8, s28, s42
	s_addc_u32 s93, s22, s43
	s_and_b32 s9, s93, 0xffff
	s_mov_b32 m0, s65
	s_nop 0
	buffer_load_dwordx4 v207, s[8:11], 0 offen lds
	s_mov_b32 m0, s67
	s_nop 0
	buffer_load_dwordx4 v209, s[8:11], 0 offen lds
	s_waitcnt vmcnt(7)
	s_barrier
	s_setprio 1
	v_mfma_f32_16x16x32_bf16 v[60:63], v[176:179], v[144:147], 0
	v_mfma_f32_16x16x32_bf16 v[56:59], v[188:191], v[144:147], 0
	v_mfma_f32_16x16x32_bf16 v[44:47], v[176:179], v[152:155], 0
	v_mfma_f32_16x16x32_bf16 v[40:43], v[188:191], v[152:155], 0
	v_mfma_f32_16x16x32_bf16 v[28:31], v[176:179], v[160:163], 0
	v_mfma_f32_16x16x32_bf16 v[24:27], v[188:191], v[160:163], 0
	v_mfma_f32_16x16x32_bf16 v[12:15], v[176:179], v[168:171], 0
	v_mfma_f32_16x16x32_bf16 v[8:11], v[188:191], v[168:171], 0
	v_mfma_f32_16x16x32_bf16 v[60:63], v[180:183], v[148:151], v[60:63]
	v_mfma_f32_16x16x32_bf16 v[56:59], v[192:195], v[148:151], v[56:59]
	v_mfma_f32_16x16x32_bf16 v[44:47], v[180:183], v[156:159], v[44:47]
	v_mfma_f32_16x16x32_bf16 v[40:43], v[192:195], v[156:159], v[40:43]
	v_mfma_f32_16x16x32_bf16 v[28:31], v[180:183], v[164:167], v[28:31]
	v_mfma_f32_16x16x32_bf16 v[24:27], v[192:195], v[164:167], v[24:27]
	v_mfma_f32_16x16x32_bf16 v[12:15], v[180:183], v[172:175], v[12:15]
	v_mfma_f32_16x16x32_bf16 v[8:11], v[192:195], v[172:175], v[8:11]
	s_setprio 0
	s_barrier
	s_branch .Lkmid_627
.LBB0_627:
	ds_read_b128 v[128:131], v212
	ds_read_b128 v[132:135], v212 offset:1024
	ds_read_b128 v[136:139], v212 offset:2048
	ds_read_b128 v[140:143], v212 offset:3072
	s_add_i32 s16, s8, 2
	s_cmp_eq_u32 s82, s8
	s_cselect_b32 s36, s1, s89
	s_cselect_b32 s23, s0, s90
	s_cselect_b32 s22, s47, s92
	s_cselect_b32 s28, s51, s91
	s_add_u32 s24, s36, 0x80
	s_addc_u32 s17, s23, 0
	s_add_u32 s8, s89, s18
	s_addc_u32 s9, s90, s19
	s_add_u32 s8, s8, 0xffffff80
	s_addc_u32 s9, s9, -1
	s_and_b32 s9, s9, 0xffff
	s_mov_b32 m0, s83
	ds_read_b128 v[144:147], v213
	ds_read_b128 v[148:151], v213 offset:1024
	ds_read_b128 v[152:155], v213 offset:2048
	ds_read_b128 v[156:159], v213 offset:3072
	ds_read_b128 v[160:163], v213 offset:4096
	ds_read_b128 v[164:167], v213 offset:5120
	ds_read_b128 v[168:171], v213 offset:6144
	ds_read_b128 v[172:175], v213 offset:7168
	buffer_load_dwordx4 v206, s[8:11], 0 offen lds
	s_mov_b32 m0, s84
	s_nop 0
	buffer_load_dwordx4 v208, s[8:11], 0 offen lds
	s_mov_b32 exec_lo, 0xffff
	s_mov_b32 exec_hi, 0
	global_load_dword v230, v[226:227], off
	s_mov_b64 exec, -1
	v_lshl_add_u64 v[226:227], v[228:229], 0, v[226:227]
	s_waitcnt lgkmcnt(8)
	s_barrier
	s_waitcnt lgkmcnt(0)
	s_setprio 1
	s_waitcnt lgkmcnt(7)
	v_mfma_f32_16x16x32_bf16 v[112:115], v[128:131], v[144:147], v[112:115]
	v_mfma_f32_16x16x32_bf16 v[116:119], v[136:139], v[144:147], v[116:119]
	s_waitcnt lgkmcnt(5)
	v_mfma_f32_16x16x32_bf16 v[100:103], v[128:131], v[152:155], v[100:103]
	v_mfma_f32_16x16x32_bf16 v[96:99], v[136:139], v[152:155], v[96:99]
	s_waitcnt lgkmcnt(3)
	v_mfma_f32_16x16x32_bf16 v[84:87], v[128:131], v[160:163], v[84:87]
	v_mfma_f32_16x16x32_bf16 v[80:83], v[136:139], v[160:163], v[80:83]
	s_waitcnt lgkmcnt(1)
	v_mfma_f32_16x16x32_bf16 v[68:71], v[128:131], v[168:171], v[68:71]
	v_mfma_f32_16x16x32_bf16 v[64:67], v[136:139], v[168:171], v[64:67]
	v_mfma_f32_16x16x32_bf16 v[112:115], v[132:135], v[148:151], v[112:115]
	v_mfma_f32_16x16x32_bf16 v[116:119], v[140:143], v[148:151], v[116:119]
	v_mfma_f32_16x16x32_bf16 v[100:103], v[132:135], v[156:159], v[100:103]
	v_mfma_f32_16x16x32_bf16 v[96:99], v[140:143], v[156:159], v[96:99]
	v_mfma_f32_16x16x32_bf16 v[84:87], v[132:135], v[164:167], v[84:87]
	v_mfma_f32_16x16x32_bf16 v[80:83], v[140:143], v[164:167], v[80:83]
	s_waitcnt lgkmcnt(0)
	v_mfma_f32_16x16x32_bf16 v[68:71], v[132:135], v[172:175], v[68:71]
	v_mfma_f32_16x16x32_bf16 v[64:67], v[140:143], v[172:175], v[64:67]
	s_setprio 0
	s_barrier
; #define PG8_STAGE(bufoff, gbase, voff) do { const __amdgpu_buffer_rsrc_t _r = __builtin_amdgcn_make_buffer_rsrc((void*)(gbase), (short)0, 0x7fffffff, 0x00020000); _Pragma("unroll") for (int _i = 0; _i < 2; ++_i) \
;         __builtin_amdgcn_raw_ptr_buffer_load_lds(_r, (LAS unsigned*)(lds + (bufoff) + ldsw + _i * 8192), 16, (int)(voff)[_i], 0, 0, 0); } while (0)
; #define PG8_LDA(dst, b, h) do { _Pragma("unroll") for (int m = 0; m < 4; ++m) _Pragma("unroll") for (int k = 0; k < 2; ++k) dst[m][k] = *(const LAS bf16x8*)(lds + PG8_SA(b, h) + aoff + m * 2048 + k * 1024); } while (0)
; #define PG8_LDB(dst, b, h) do { _Pragma("unroll") for (int n = 0; n < 2; ++n) _Pragma("unroll") for (int k = 0; k < 2; ++k) dst[n][k] = *(const LAS bf16x8*)(lds + PG8_SB(b, h) + boff + n * 2048 + k * 1024); } while (0)
; #define PG8_MMA(ai, bj, At, Bt) do { __builtin_amdgcn_s_setprio(1); _Pragma("unroll") for (int k = 0; k < 2; ++k) _Pragma("unroll") for (int m = 0; m < 4; ++m) _Pragma("unroll") for (int n = 0; n < ((bj) == 1 ? NB1 : 2); ++n) \
;         acc[ai][bj][m][n] = __builtin_amdgcn_mfma_f32_16x16x32_bf16(Bt[n][k], At[m][k], acc[ai][bj][m][n], 0, 0, 0); __builtin_amdgcn_s_setprio(0); } while (0)
; #define PG8_WAIT_V(n) asm volatile("s_waitcnt vmcnt(" #n ")" ::: "memory")
; #define PG8_WAIT_L(n) asm volatile("s_waitcnt lgkmcnt(" #n ")" ::: "memory")
; #define PG8_BAR __builtin_amdgcn_s_barrier()
; #define PG8_SCHED __builtin_amdgcn_sched_barrier(0)
;     ...
;             PG8_LDB(B1, 0, 1); PG8_STAGE(PG8_SB(0, 0), b2, voffB);
;             PG8_BAR; PG8_WAIT_L(0); PG8_MMA(0, 1, At, B1); PG8_BAR;
;             PG8_LDA(At, 0, 1); PG8_STAGE(PG8_SA(0, 0), a2, voffA);
;             PG8_BAR; PG8_WAIT_L(0); PG8_MMA(1, 0, At, B0); PG8_BAR; PG8_SCHED;
;             PG8_STAGE(PG8_SB(0, 1), b2 + hstepB, voffB);
;             PG8_WAIT_V(6); PG8_BAR; PG8_MMA(1, 1, At, B1); PG8_BAR;
	s_and_b32 s29, s22, 0xffff
	s_mov_b32 s30, s10
	s_mov_b32 s31, s11
	s_mov_b32 m0, s15
	ds_read_b128 v[176:179], v214
	ds_read_b128 v[180:183], v214 offset:1024
	ds_read_b128 v[188:191], v214 offset:2048
	ds_read_b128 v[192:195], v214 offset:3072
	buffer_load_dwordx4 v207, s[28:31], 0 offen lds
	s_mov_b32 m0, s33
	s_nop 0
	buffer_load_dwordx4 v209, s[28:31], 0 offen lds
	s_barrier
	s_waitcnt lgkmcnt(0)
	s_setprio 1
	s_waitcnt lgkmcnt(3)
	v_mfma_f32_16x16x32_bf16 v[124:127], v[176:179], v[144:147], v[124:127]
	s_waitcnt lgkmcnt(1)
	v_mfma_f32_16x16x32_bf16 v[120:123], v[188:191], v[144:147], v[120:123]
	v_mfma_f32_16x16x32_bf16 v[108:111], v[176:179], v[152:155], v[108:111]
	v_mfma_f32_16x16x32_bf16 v[104:107], v[188:191], v[152:155], v[104:107]
	v_mfma_f32_16x16x32_bf16 v[92:95], v[176:179], v[160:163], v[92:95]
	v_mfma_f32_16x16x32_bf16 v[88:91], v[188:191], v[160:163], v[88:91]
	v_mfma_f32_16x16x32_bf16 v[76:79], v[176:179], v[168:171], v[76:79]
	v_mfma_f32_16x16x32_bf16 v[72:75], v[188:191], v[168:171], v[72:75]
	v_mfma_f32_16x16x32_bf16 v[124:127], v[180:183], v[148:151], v[124:127]
	s_waitcnt lgkmcnt(0)
	v_mfma_f32_16x16x32_bf16 v[120:123], v[192:195], v[148:151], v[120:123]
	v_mfma_f32_16x16x32_bf16 v[108:111], v[180:183], v[156:159], v[108:111]
	v_mfma_f32_16x16x32_bf16 v[104:107], v[192:195], v[156:159], v[104:107]
	v_mfma_f32_16x16x32_bf16 v[92:95], v[180:183], v[164:167], v[92:95]
	v_mfma_f32_16x16x32_bf16 v[88:91], v[192:195], v[164:167], v[88:91]
	v_mfma_f32_16x16x32_bf16 v[76:79], v[180:183], v[172:175], v[76:79]
	v_mfma_f32_16x16x32_bf16 v[72:75], v[192:195], v[172:175], v[72:75]
	s_setprio 0
	s_and_b32 s37, s23, 0xffff
	s_mov_b32 s38, s10
	s_mov_b32 s39, s11
	s_mov_b32 m0, s14
	s_barrier
	ds_read_b128 v[144:147], v213 offset:16384
	ds_read_b128 v[148:151], v213 offset:17408
	ds_read_b128 v[152:155], v213 offset:18432
	ds_read_b128 v[156:159], v213 offset:19456
	ds_read_b128 v[160:163], v213 offset:20480
	ds_read_b128 v[164:167], v213 offset:21504
	ds_read_b128 v[168:171], v213 offset:22528
	ds_read_b128 v[172:175], v213 offset:23552
	buffer_load_dwordx4 v206, s[36:39], 0 offen lds
	s_mov_b32 m0, s35
	s_nop 0
	buffer_load_dwordx4 v208, s[36:39], 0 offen lds
	s_barrier
	s_waitcnt lgkmcnt(0)
	s_setprio 1
	s_waitcnt lgkmcnt(7)
	v_mfma_f32_16x16x32_bf16 v[52:55], v[128:131], v[144:147], v[52:55]
	v_mfma_f32_16x16x32_bf16 v[48:51], v[136:139], v[144:147], v[48:51]
	s_waitcnt lgkmcnt(5)
	v_mfma_f32_16x16x32_bf16 v[36:39], v[128:131], v[152:155], v[36:39]
	v_mfma_f32_16x16x32_bf16 v[32:35], v[136:139], v[152:155], v[32:35]
	s_waitcnt lgkmcnt(3)
	v_mfma_f32_16x16x32_bf16 v[20:23], v[128:131], v[160:163], v[20:23]
	v_mfma_f32_16x16x32_bf16 v[16:19], v[136:139], v[160:163], v[16:19]
	s_waitcnt lgkmcnt(1)
	v_mfma_f32_16x16x32_bf16 v[4:7], v[128:131], v[168:171], v[4:7]
	v_mfma_f32_16x16x32_bf16 v[0:3], v[136:139], v[168:171], v[0:3]
	v_mfma_f32_16x16x32_bf16 v[52:55], v[132:135], v[148:151], v[52:55]
	v_mfma_f32_16x16x32_bf16 v[48:51], v[140:143], v[148:151], v[48:51]
	v_mfma_f32_16x16x32_bf16 v[36:39], v[132:135], v[156:159], v[36:39]
	v_mfma_f32_16x16x32_bf16 v[32:35], v[140:143], v[156:159], v[32:35]
	v_mfma_f32_16x16x32_bf16 v[20:23], v[132:135], v[164:167], v[20:23]
	v_mfma_f32_16x16x32_bf16 v[16:19], v[140:143], v[164:167], v[16:19]
	s_waitcnt lgkmcnt(0)
	v_mfma_f32_16x16x32_bf16 v[4:7], v[132:135], v[172:175], v[4:7]
	v_mfma_f32_16x16x32_bf16 v[0:3], v[140:143], v[172:175], v[0:3]
	s_setprio 0
	s_barrier
	s_add_u32 s8, s28, s42
	s_addc_u32 s93, s22, s43
	s_and_b32 s9, s93, 0xffff
	s_mov_b32 m0, s65
	s_nop 0
	buffer_load_dwordx4 v207, s[8:11], 0 offen lds
	s_mov_b32 m0, s67
	s_nop 0
	buffer_load_dwordx4 v209, s[8:11], 0 offen lds
	s_waitcnt vmcnt(7)
	s_barrier
	s_setprio 1
	v_mfma_f32_16x16x32_bf16 v[60:63], v[176:179], v[144:147], v[60:63]
	v_mfma_f32_16x16x32_bf16 v[56:59], v[188:191], v[144:147], v[56:59]
	v_mfma_f32_16x16x32_bf16 v[44:47], v[176:179], v[152:155], v[44:47]
	v_mfma_f32_16x16x32_bf16 v[40:43], v[188:191], v[152:155], v[40:43]
	v_mfma_f32_16x16x32_bf16 v[28:31], v[176:179], v[160:163], v[28:31]
	v_mfma_f32_16x16x32_bf16 v[24:27], v[188:191], v[160:163], v[24:27]
	v_mfma_f32_16x16x32_bf16 v[12:15], v[176:179], v[168:171], v[12:15]
	v_mfma_f32_16x16x32_bf16 v[8:11], v[188:191], v[168:171], v[8:11]
	v_mfma_f32_16x16x32_bf16 v[60:63], v[180:183], v[148:151], v[60:63]
	v_mfma_f32_16x16x32_bf16 v[56:59], v[192:195], v[148:151], v[56:59]
	v_mfma_f32_16x16x32_bf16 v[44:47], v[180:183], v[156:159], v[44:47]
	v_mfma_f32_16x16x32_bf16 v[40:43], v[192:195], v[156:159], v[40:43]
	v_mfma_f32_16x16x32_bf16 v[28:31], v[180:183], v[164:167], v[28:31]
	v_mfma_f32_16x16x32_bf16 v[24:27], v[192:195], v[164:167], v[24:27]
	v_mfma_f32_16x16x32_bf16 v[12:15], v[180:183], v[172:175], v[12:15]
	v_mfma_f32_16x16x32_bf16 v[8:11], v[192:195], v[172:175], v[8:11]
	s_setprio 0
	s_barrier
